# grid barrier: each XCD leader releases its local workgroups before issuing its own cache invalidate (was invalidate, then release); on v61
# baseline (speedup 1.0000x reference)
; __device__ __forceinline__ unsigned xb_add(unsigned* p, unsigned v) { return __hip_atomic_fetch_add(p, v, __ATOMIC_RELAXED, __HIP_MEMORY_SCOPE_AGENT); }
; __device__ __forceinline__ void xcd_barrier(const XcdBarrier& b) {
;     ...
;             __builtin_amdgcn_fence(__ATOMIC_ACQUIRE, "agent");
;             xb_add(&bar[XB_XGEN(b.x)], 1u);
;             asm volatile("s_waitcnt vmcnt(0)" ::: "memory");
.LBB0_132:
	s_or_b64 exec, exec, s[4:5]
	v_add_co_u32_e32 v0, vcc, 0x2000, v2
	v_mov_b32_e32 v2, 1
	s_nop 0
	v_addc_co_u32_e32 v1, vcc, 0, v3, vcc
	s_waitcnt vmcnt(0)
	global_atomic_add v[0:1], v2, off offset:1024
	buffer_inv sc1
	s_waitcnt vmcnt(0)

; __device__ __forceinline__ unsigned xb_add(unsigned* p, unsigned v) { return __hip_atomic_fetch_add(p, v, __ATOMIC_RELAXED, __HIP_MEMORY_SCOPE_AGENT); }
; __device__ __forceinline__ void xcd_barrier(const XcdBarrier& b) {
;     ...
;             __builtin_amdgcn_fence(__ATOMIC_ACQUIRE, "agent");
;             xb_add(&bar[XB_XGEN(b.x)], 1u);
;             asm volatile("s_waitcnt vmcnt(0)" ::: "memory");
.LBB0_266:
	s_or_b64 exec, exec, s[4:5]
	v_add_co_u32_e32 v0, vcc, 0x2000, v2
	s_waitcnt vmcnt(0)
	v_addc_co_u32_e32 v1, vcc, 0, v3, vcc
	global_atomic_add v[0:1], v195, off offset:1024
	buffer_inv sc1
	s_waitcnt vmcnt(0)
